# as v53 + in-proj K-loop: the two LDS-DMA loads of each 12-read load segment issued one segment later (after its 4 reads), DMA issue order unchanged
# baseline (speedup 1.0000x reference)
; #define PG8_STAGE(bufoff, gbase, voff) do { _Pragma("unroll") for (int _i = 0; _i < 2; ++_i) \
;         __builtin_amdgcn_global_load_lds((const unsigned*)((const char*)(gbase) + (voff)[_i]), (LAS unsigned*)(lds + (bufoff) + ldsw + _i * 8192), 16, 0, 0); } while (0)
; #define PG8_LDA(dst, b, h) do { _Pragma("unroll") for (int m = 0; m < 4; ++m) _Pragma("unroll") for (int k = 0; k < 2; ++k) dst[m][k] = *(const LAS bf16x8*)(lds + PG8_SA(b, h) + aoff + m * 2048 + k * 1024); } while (0)
; #define PG8_LDB(dst, b, h) do { _Pragma("unroll") for (int n = 0; n < 2; ++n) _Pragma("unroll") for (int k = 0; k < 2; ++k) dst[n][k] = *(const LAS bf16x8*)(lds + PG8_SB(b, h) + boff + n * 2048 + k * 1024); } while (0)
; #define PG8_MMA(ai, bj, At, Bt) do { __builtin_amdgcn_s_setprio(1); _Pragma("unroll") for (int m = 0; m < 4; ++m) _Pragma("unroll") for (int n = 0; n < 2; ++n) _Pragma("unroll") for (int k = 0; k < 2; ++k) \
;         acc[ai][bj][m][n] = __builtin_amdgcn_mfma_f32_16x16x32_bf16(Bt[n][k], At[m][k], acc[ai][bj][m][n], 0, 0, 0); __builtin_amdgcn_s_setprio(0); } while (0)
; #define PG8_WAIT_V(n) asm volatile("s_waitcnt vmcnt(" #n ")" ::: "memory")
; #define PG8_WAIT_L(n) asm volatile("s_waitcnt lgkmcnt(" #n ")" ::: "memory")
; #define PG8_BAR __builtin_amdgcn_s_barrier()
; #define PG8_SCHED __builtin_amdgcn_sched_barrier(0)
; template <class Epi>
; __device__ __forceinline__ void gemm_phase(LAS unsigned char* lds, const Gemm g, const StaticOrder& S, const Epi& E) {
;     ...
;             PG8_LDB(B0, 0, 0); PG8_SCHED; PG8_LDA(At, 0, 0); PG8_STAGE(PG8_SA(1, 1), a1 + hstepA, voffA);
;             PG8_WAIT_L(8); PG8_BAR; PG8_WAIT_L(0); PG8_MMA(0, 0, At, B0); PG8_BAR; PG8_SCHED;
;             PG8_LDB(B1, 0, 1); PG8_STAGE(PG8_SB(0, 0), b2, voffB);
;             PG8_BAR; PG8_WAIT_L(0); PG8_MMA(0, 1, At, B1); PG8_BAR;
;             PG8_LDA(At, 0, 1); PG8_STAGE(PG8_SA(0, 0), a2, voffA);
;             PG8_BAR; PG8_WAIT_L(0); PG8_MMA(1, 0, At, B0); PG8_BAR; PG8_SCHED;
;             PG8_STAGE(PG8_SB(0, 1), b2 + hstepB, voffB);
;             PG8_WAIT_V(6); PG8_BAR; PG8_MMA(1, 1, At, B1); PG8_BAR;
.LBB0_158:
	s_add_u32 s42, s38, 0x100
	s_addc_u32 s43, s39, 0
	s_add_i32 s60, 0, 0x10000
	ds_read_b128 v[146:149], v250
	ds_read_b128 v[162:165], v250 offset:1024
	ds_read_b128 v[166:169], v250 offset:2048
	ds_read_b128 v[170:173], v250 offset:3072
	s_cmp_eq_u32 s59, 28
	s_cselect_b32 s25, s23, s43
	s_cselect_b32 s24, s55, s42
	s_cselect_b32 s5, s21, s58
	s_cselect_b32 s4, s56, s57
	ds_read_b128 v[174:177], v154
	ds_read_b128 v[188:191], v154 offset:1024
	ds_read_b128 v[192:195], v154 offset:2048
	ds_read_b128 v[196:199], v154 offset:3072
	ds_read_b128 v[200:203], v154 offset:4096
	ds_read_b128 v[204:207], v154 offset:5120
	ds_read_b128 v[208:211], v154 offset:6144
	ds_read_b128 v[212:215], v154 offset:7168
	s_waitcnt lgkmcnt(8)
	s_barrier
	s_waitcnt lgkmcnt(0)
	v_mfma_f32_16x16x32_bf16 v[126:129], v[146:149], v[174:177], v[126:129]
	v_mfma_f32_16x16x32_bf16 v[122:125], v[166:169], v[174:177], v[122:125]
	v_mfma_f32_16x16x32_bf16 v[110:113], v[146:149], v[192:195], v[110:113]
	v_mfma_f32_16x16x32_bf16 v[106:109], v[166:169], v[192:195], v[106:109]
	v_mfma_f32_16x16x32_bf16 v[94:97], v[146:149], v[200:203], v[94:97]
	v_mfma_f32_16x16x32_bf16 v[90:93], v[166:169], v[200:203], v[90:93]
	v_mfma_f32_16x16x32_bf16 v[78:81], v[146:149], v[208:211], v[78:81]
	v_mfma_f32_16x16x32_bf16 v[74:77], v[166:169], v[208:211], v[74:77]
	v_mfma_f32_16x16x32_bf16 v[126:129], v[162:165], v[188:191], v[126:129]
	v_mfma_f32_16x16x32_bf16 v[122:125], v[170:173], v[188:191], v[122:125]
	v_mfma_f32_16x16x32_bf16 v[110:113], v[162:165], v[196:199], v[110:113]
	v_mfma_f32_16x16x32_bf16 v[106:109], v[170:173], v[196:199], v[106:109]
	v_mfma_f32_16x16x32_bf16 v[94:97], v[162:165], v[204:207], v[94:97]
	v_mfma_f32_16x16x32_bf16 v[90:93], v[170:173], v[204:207], v[90:93]
	v_mfma_f32_16x16x32_bf16 v[78:81], v[162:165], v[212:215], v[78:81]
	v_mfma_f32_16x16x32_bf16 v[74:77], v[170:173], v[212:215], v[74:77]
	s_barrier
	ds_read_b128 v[216:219], v250 offset:16384
	ds_read_b128 v[220:223], v250 offset:17408
	ds_read_b128 v[224:227], v250 offset:18432
	ds_read_b128 v[228:231], v250 offset:19456
	s_add_i32 m0, s46, 0xc000
	s_nop 0
	global_load_lds_dwordx4 v140, s[38:39]
	s_add_i32 m0, s46, 0xe000
	s_nop 0
	global_load_lds_dwordx4 v142, s[38:39]
	s_add_i32 s61, 0, 0x14000
	s_add_i32 s38, s60, s45
	s_add_u32 s100, s4, s6
	s_addc_u32 s101, s5, s7
	s_mov_b32 m0, s38
	global_load_lds_dwordx4 v134, s[4:5]
	s_add_i32 m0, s38, 0x2000
	s_nop 0
	global_load_lds_dwordx4 v130, s[4:5]
	s_barrier
	s_waitcnt lgkmcnt(0)
	v_mfma_f32_16x16x32_bf16 v[118:121], v[216:219], v[174:177], v[118:121]
	v_mfma_f32_16x16x32_bf16 v[114:117], v[224:227], v[174:177], v[114:117]
	v_mfma_f32_16x16x32_bf16 v[102:105], v[216:219], v[192:195], v[102:105]
	v_mfma_f32_16x16x32_bf16 v[98:101], v[224:227], v[192:195], v[98:101]
	v_mfma_f32_16x16x32_bf16 v[86:89], v[216:219], v[200:203], v[86:89]
	v_mfma_f32_16x16x32_bf16 v[82:85], v[224:227], v[200:203], v[82:85]
	v_mfma_f32_16x16x32_bf16 v[70:73], v[216:219], v[208:211], v[70:73]
	v_mfma_f32_16x16x32_bf16 v[66:69], v[224:227], v[208:211], v[66:69]
	v_mfma_f32_16x16x32_bf16 v[118:121], v[220:223], v[188:191], v[118:121]
	v_mfma_f32_16x16x32_bf16 v[114:117], v[228:231], v[188:191], v[114:117]
	v_mfma_f32_16x16x32_bf16 v[102:105], v[220:223], v[196:199], v[102:105]
	v_mfma_f32_16x16x32_bf16 v[98:101], v[228:231], v[196:199], v[98:101]
	v_mfma_f32_16x16x32_bf16 v[86:89], v[220:223], v[204:207], v[86:89]
	v_mfma_f32_16x16x32_bf16 v[82:85], v[228:231], v[204:207], v[82:85]
	v_mfma_f32_16x16x32_bf16 v[70:73], v[220:223], v[212:215], v[70:73]
	v_mfma_f32_16x16x32_bf16 v[66:69], v[228:231], v[212:215], v[66:69]
	s_mov_b32 m0, s46
	s_add_u32 vcc_lo, s24, s6
	s_addc_u32 vcc_hi, s25, s7
	s_barrier
	ds_read_b128 v[174:177], v154 offset:16384
	ds_read_b128 v[188:191], v154 offset:17408
	ds_read_b128 v[192:195], v154 offset:18432
	ds_read_b128 v[196:199], v154 offset:19456
	ds_read_b128 v[200:203], v154 offset:20480
	ds_read_b128 v[204:207], v154 offset:21504
	ds_read_b128 v[208:211], v154 offset:22528
	ds_read_b128 v[212:215], v154 offset:23552
	global_load_lds_dwordx4 v136, s[24:25]
	s_mov_b32 m0, s47
	s_nop 0
	global_load_lds_dwordx4 v132, s[24:25]
	s_barrier
	s_waitcnt lgkmcnt(0)
	v_mfma_f32_16x16x32_bf16 v[62:65], v[146:149], v[174:177], v[62:65]
	v_mfma_f32_16x16x32_bf16 v[58:61], v[166:169], v[174:177], v[58:61]
	v_mfma_f32_16x16x32_bf16 v[46:49], v[146:149], v[192:195], v[46:49]
	v_mfma_f32_16x16x32_bf16 v[42:45], v[166:169], v[192:195], v[42:45]
	v_mfma_f32_16x16x32_bf16 v[30:33], v[146:149], v[200:203], v[30:33]
	v_mfma_f32_16x16x32_bf16 v[26:29], v[166:169], v[200:203], v[26:29]
	v_mfma_f32_16x16x32_bf16 v[14:17], v[146:149], v[208:211], v[14:17]
	v_mfma_f32_16x16x32_bf16 v[10:13], v[166:169], v[208:211], v[10:13]
	v_mfma_f32_16x16x32_bf16 v[62:65], v[162:165], v[188:191], v[62:65]
	v_mfma_f32_16x16x32_bf16 v[58:61], v[170:173], v[188:191], v[58:61]
	v_mfma_f32_16x16x32_bf16 v[46:49], v[162:165], v[196:199], v[46:49]
	v_mfma_f32_16x16x32_bf16 v[42:45], v[170:173], v[196:199], v[42:45]
	v_mfma_f32_16x16x32_bf16 v[30:33], v[162:165], v[204:207], v[30:33]
	v_mfma_f32_16x16x32_bf16 v[26:29], v[170:173], v[204:207], v[26:29]
	v_mfma_f32_16x16x32_bf16 v[14:17], v[162:165], v[212:215], v[14:17]
	v_mfma_f32_16x16x32_bf16 v[10:13], v[170:173], v[212:215], v[10:13]
	s_barrier
	s_add_u32 s38, s4, 0x80000
	s_addc_u32 s39, s5, 0
	s_add_i32 s60, s61, s45
	s_mov_b32 m0, s60
	s_nop 0
	global_load_lds_dwordx4 v134, s[38:39]
	s_add_i32 m0, s60, 0x2000
	s_nop 0
	global_load_lds_dwordx4 v130, s[38:39]
	s_waitcnt vmcnt(6)
	s_barrier
; #define PG8_STAGE(bufoff, gbase, voff) do { _Pragma("unroll") for (int _i = 0; _i < 2; ++_i) \
;         __builtin_amdgcn_global_load_lds((const unsigned*)((const char*)(gbase) + (voff)[_i]), (LAS unsigned*)(lds + (bufoff) + ldsw + _i * 8192), 16, 0, 0); } while (0)
; #define PG8_LDA(dst, b, h) do { _Pragma("unroll") for (int m = 0; m < 4; ++m) _Pragma("unroll") for (int k = 0; k < 2; ++k) dst[m][k] = *(const LAS bf16x8*)(lds + PG8_SA(b, h) + aoff + m * 2048 + k * 1024); } while (0)
; #define PG8_LDB(dst, b, h) do { _Pragma("unroll") for (int n = 0; n < 2; ++n) _Pragma("unroll") for (int k = 0; k < 2; ++k) dst[n][k] = *(const LAS bf16x8*)(lds + PG8_SB(b, h) + boff + n * 2048 + k * 1024); } while (0)
; #define PG8_MMA(ai, bj, At, Bt) do { __builtin_amdgcn_s_setprio(1); _Pragma("unroll") for (int m = 0; m < 4; ++m) _Pragma("unroll") for (int n = 0; n < 2; ++n) _Pragma("unroll") for (int k = 0; k < 2; ++k) \
;         acc[ai][bj][m][n] = __builtin_amdgcn_mfma_f32_16x16x32_bf16(Bt[n][k], At[m][k], acc[ai][bj][m][n], 0, 0, 0); __builtin_amdgcn_s_setprio(0); } while (0)
; #define PG8_WAIT_V(n) asm volatile("s_waitcnt vmcnt(" #n ")" ::: "memory")
; #define PG8_WAIT_L(n) asm volatile("s_waitcnt lgkmcnt(" #n ")" ::: "memory")
; #define PG8_BAR __builtin_amdgcn_s_barrier()
; #define PG8_SCHED __builtin_amdgcn_sched_barrier(0)
; template <class Epi>
; __device__ __forceinline__ void gemm_phase(LAS unsigned char* lds, const Gemm g, const StaticOrder& S, const Epi& E) {
;     ...
;             PG8_WAIT_V(6); PG8_BAR; PG8_MMA(1, 1, At, B1); PG8_BAR;
;             PG8_LDB(B0, 1, 0); PG8_SCHED; PG8_LDA(At, 1, 0); PG8_STAGE(PG8_SA(0, 1), a2 + hstepA, voffA);
;             PG8_WAIT_L(8); PG8_BAR; PG8_WAIT_L(0); PG8_MMA(0, 0, At, B0); PG8_BAR; PG8_SCHED;
;             PG8_LDB(B1, 1, 1); PG8_STAGE(PG8_SB(1, 0), b3, voffB);
;             PG8_BAR; PG8_WAIT_L(0); PG8_MMA(0, 1, At, B1); PG8_BAR;
	v_mfma_f32_16x16x32_bf16 v[54:57], v[216:219], v[174:177], v[54:57]
	v_mfma_f32_16x16x32_bf16 v[50:53], v[224:227], v[174:177], v[50:53]
	v_mfma_f32_16x16x32_bf16 v[38:41], v[216:219], v[192:195], v[38:41]
	v_mfma_f32_16x16x32_bf16 v[34:37], v[224:227], v[192:195], v[34:37]
	v_mfma_f32_16x16x32_bf16 v[22:25], v[216:219], v[200:203], v[22:25]
	v_mfma_f32_16x16x32_bf16 v[18:21], v[224:227], v[200:203], v[18:21]
	v_mfma_f32_16x16x32_bf16 v[6:9], v[216:219], v[208:211], v[6:9]
	v_mfma_f32_16x16x32_bf16 v[2:5], v[224:227], v[208:211], v[2:5]
	v_mfma_f32_16x16x32_bf16 v[54:57], v[220:223], v[188:191], v[54:57]
	v_mfma_f32_16x16x32_bf16 v[50:53], v[228:231], v[188:191], v[50:53]
	v_mfma_f32_16x16x32_bf16 v[38:41], v[220:223], v[196:199], v[38:41]
	v_mfma_f32_16x16x32_bf16 v[34:37], v[228:231], v[196:199], v[34:37]
	v_mfma_f32_16x16x32_bf16 v[22:25], v[220:223], v[204:207], v[22:25]
	v_mfma_f32_16x16x32_bf16 v[18:21], v[228:231], v[204:207], v[18:21]
	v_mfma_f32_16x16x32_bf16 v[6:9], v[220:223], v[212:215], v[6:9]
	v_mfma_f32_16x16x32_bf16 v[2:5], v[228:231], v[212:215], v[2:5]
	s_add_i32 s38, 0, 0x18000
	s_barrier
	ds_read_b128 v[146:149], v250 offset:32768
	ds_read_b128 v[162:165], v250 offset:33792
	ds_read_b128 v[166:169], v250 offset:34816
	ds_read_b128 v[170:173], v250 offset:35840
	s_add_u32 s24, s24, 0x80000
	s_addc_u32 s25, s25, 0
	ds_read_b128 v[174:177], v154 offset:32768
	ds_read_b128 v[188:191], v154 offset:33792
	ds_read_b128 v[192:195], v154 offset:34816
	ds_read_b128 v[196:199], v154 offset:35840
	ds_read_b128 v[200:203], v154 offset:36864
	ds_read_b128 v[204:207], v154 offset:37888
	ds_read_b128 v[208:211], v154 offset:38912
	ds_read_b128 v[212:215], v154 offset:39936
	s_waitcnt lgkmcnt(8)
	s_barrier
	s_waitcnt lgkmcnt(0)
	v_mfma_f32_16x16x32_bf16 v[126:129], v[146:149], v[174:177], v[126:129]
	v_mfma_f32_16x16x32_bf16 v[122:125], v[166:169], v[174:177], v[122:125]
	v_mfma_f32_16x16x32_bf16 v[110:113], v[146:149], v[192:195], v[110:113]
	v_mfma_f32_16x16x32_bf16 v[106:109], v[166:169], v[192:195], v[106:109]
	v_mfma_f32_16x16x32_bf16 v[94:97], v[146:149], v[200:203], v[94:97]
	v_mfma_f32_16x16x32_bf16 v[90:93], v[166:169], v[200:203], v[90:93]
	v_mfma_f32_16x16x32_bf16 v[78:81], v[146:149], v[208:211], v[78:81]
	v_mfma_f32_16x16x32_bf16 v[74:77], v[166:169], v[208:211], v[74:77]
	v_mfma_f32_16x16x32_bf16 v[126:129], v[162:165], v[188:191], v[126:129]
	v_mfma_f32_16x16x32_bf16 v[122:125], v[170:173], v[188:191], v[122:125]
	v_mfma_f32_16x16x32_bf16 v[110:113], v[162:165], v[196:199], v[110:113]
	v_mfma_f32_16x16x32_bf16 v[106:109], v[170:173], v[196:199], v[106:109]
	v_mfma_f32_16x16x32_bf16 v[94:97], v[162:165], v[204:207], v[94:97]
	v_mfma_f32_16x16x32_bf16 v[90:93], v[170:173], v[204:207], v[90:93]
	v_mfma_f32_16x16x32_bf16 v[78:81], v[162:165], v[212:215], v[78:81]
	v_mfma_f32_16x16x32_bf16 v[74:77], v[170:173], v[212:215], v[74:77]
	s_barrier
	ds_read_b128 v[216:219], v250 offset:49152
	ds_read_b128 v[220:223], v250 offset:50176
	ds_read_b128 v[224:227], v250 offset:51200
	ds_read_b128 v[228:231], v250 offset:52224
	s_mov_b32 m0, s48
	s_nop 0
	global_load_lds_dwordx4 v136, s[24:25]
	s_mov_b32 m0, s49
	s_nop 0
	global_load_lds_dwordx4 v132, s[24:25]
	s_add_i32 s24, 0, 0x1c000
	s_add_i32 s25, s38, s45
	s_mov_b32 m0, s25
	global_load_lds_dwordx4 v134, s[100:101]
	s_add_i32 m0, s25, 0x2000
	s_nop 0
	global_load_lds_dwordx4 v130, s[100:101]
	s_barrier
	s_waitcnt lgkmcnt(0)
	v_mfma_f32_16x16x32_bf16 v[118:121], v[216:219], v[174:177], v[118:121]
	v_mfma_f32_16x16x32_bf16 v[114:117], v[224:227], v[174:177], v[114:117]
	v_mfma_f32_16x16x32_bf16 v[102:105], v[216:219], v[192:195], v[102:105]
	v_mfma_f32_16x16x32_bf16 v[98:101], v[224:227], v[192:195], v[98:101]
	v_mfma_f32_16x16x32_bf16 v[86:89], v[216:219], v[200:203], v[86:89]
	v_mfma_f32_16x16x32_bf16 v[82:85], v[224:227], v[200:203], v[82:85]
	v_mfma_f32_16x16x32_bf16 v[70:73], v[216:219], v[208:211], v[70:73]
	v_mfma_f32_16x16x32_bf16 v[66:69], v[224:227], v[208:211], v[66:69]
	v_mfma_f32_16x16x32_bf16 v[118:121], v[220:223], v[188:191], v[118:121]
	v_mfma_f32_16x16x32_bf16 v[114:117], v[228:231], v[188:191], v[114:117]
	v_mfma_f32_16x16x32_bf16 v[102:105], v[220:223], v[196:199], v[102:105]
	v_mfma_f32_16x16x32_bf16 v[98:101], v[228:231], v[196:199], v[98:101]
	v_mfma_f32_16x16x32_bf16 v[86:89], v[220:223], v[204:207], v[86:89]
	v_mfma_f32_16x16x32_bf16 v[82:85], v[228:231], v[204:207], v[82:85]
	v_mfma_f32_16x16x32_bf16 v[70:73], v[220:223], v[212:215], v[70:73]
	v_mfma_f32_16x16x32_bf16 v[66:69], v[228:231], v[212:215], v[66:69]
	s_mov_b32 m0, s50
	s_barrier
; __device__ __forceinline__ unsigned cvt_pk_bf16(float lo, float hi) { unsigned r; asm volatile("v_cvt_pk_bf16_f32 %0, %1, %2" : "=v"(r) : "v"(lo), "v"(hi)); return r; }
; #define PG8_STAGE(bufoff, gbase, voff) do { _Pragma("unroll") for (int _i = 0; _i < 2; ++_i) \
;         __builtin_amdgcn_global_load_lds((const unsigned*)((const char*)(gbase) + (voff)[_i]), (LAS unsigned*)(lds + (bufoff) + ldsw + _i * 8192), 16, 0, 0); } while (0)
; #define PG8_LDA(dst, b, h) do { _Pragma("unroll") for (int m = 0; m < 4; ++m) _Pragma("unroll") for (int k = 0; k < 2; ++k) dst[m][k] = *(const LAS bf16x8*)(lds + PG8_SA(b, h) + aoff + m * 2048 + k * 1024); } while (0)
; #define PG8_WAIT_V(n) asm volatile("s_waitcnt vmcnt(" #n ")" ::: "memory")
; #define PG8_WAIT_L(n) asm volatile("s_waitcnt lgkmcnt(" #n ")" ::: "memory")
; #define PG8_BAR __builtin_amdgcn_s_barrier()
; #define PG8_SCHED __builtin_amdgcn_sched_barrier(0)
; template <class Epi>
; __device__ __forceinline__ void gemm_phase(LAS unsigned char* lds, const Gemm g, const StaticOrder& S, const Epi& E) {
;     ...
;             PG8_LDA(At, 1, 1); PG8_STAGE(PG8_SA(1, 0), a3, voffA);
;             PG8_BAR; PG8_WAIT_L(0); PG8_MMA(1, 0, At, B0); PG8_BAR; PG8_SCHED;
;             PG8_STAGE(PG8_SB(1, 1), b3 + hstepB, voffB);
;             PG8_WAIT_V(6); PG8_BAR; PG8_MMA(1, 1, At, B1); PG8_BAR;
;     __device__ __forceinline__ void operator()(const f32x4 (&acc)[2][2][4][2], const Unit& u, int wr, int wc, int fr, int fq, const Pre& pp) const {
;         const int row0 = u.pm * BM + wr * 64 + fr, col0 = u.pn * BM + wc * 32 + 8 * fq;
;         const bool gm = (UG != nullptr) && (u.pn < DE / BM);
;         const float (&rs)[8] = pp.rs;
; #pragma unroll
;         for (int ai = 0; ai < 2; ++ai)
; #pragma unroll
;             for (int m = 0; m < 4; ++m) { const int r = row0 + ai * HALF + m * 16; const float inv = rsqrtf(rs[ai * 4 + m] * (1.0f / DM) + EPS);
; #pragma unroll
;                 for (int bj = 0; bj < 2; ++bj) { const f32x4 v0 = acc[ai][bj][m][0] * inv, v1 = acc[ai][bj][m][1] * inv; const int c = col0 + bj * HALF;
;                     u32x4 w; w.x = cvt_pk_bf16(v0[0], v0[1]); w.y = cvt_pk_bf16(v0[2], v0[3]); w.z = cvt_pk_bf16(v1[0], v1[1]); w.w = cvt_pk_bf16(v1[2], v1[3]);
;                     bf16_t* dst = gm ? UG + (size_t)(c >> 4) * GSTR + r * 16 + (c & 15) : O + (size_t)r * DE2 + c;
	ds_read_b128 v[174:177], v154 offset:49152
	ds_read_b128 v[188:191], v154 offset:50176
	ds_read_b128 v[192:195], v154 offset:51200
	ds_read_b128 v[196:199], v154 offset:52224
	ds_read_b128 v[200:203], v154 offset:53248
	ds_read_b128 v[204:207], v154 offset:54272
	ds_read_b128 v[208:211], v154 offset:55296
	ds_read_b128 v[212:215], v154 offset:56320
	global_load_lds_dwordx4 v136, vcc
	s_mov_b32 m0, s51
	s_nop 0
	global_load_lds_dwordx4 v132, vcc
	s_barrier
	s_waitcnt lgkmcnt(0)
	v_mfma_f32_16x16x32_bf16 v[62:65], v[146:149], v[174:177], v[62:65]
	v_mfma_f32_16x16x32_bf16 v[58:61], v[166:169], v[174:177], v[58:61]
	v_mfma_f32_16x16x32_bf16 v[46:49], v[146:149], v[192:195], v[46:49]
	v_mfma_f32_16x16x32_bf16 v[42:45], v[166:169], v[192:195], v[42:45]
	v_mfma_f32_16x16x32_bf16 v[30:33], v[146:149], v[200:203], v[30:33]
	v_mfma_f32_16x16x32_bf16 v[26:29], v[166:169], v[200:203], v[26:29]
	v_mfma_f32_16x16x32_bf16 v[14:17], v[146:149], v[208:211], v[14:17]
	v_mfma_f32_16x16x32_bf16 v[10:13], v[166:169], v[208:211], v[10:13]
	v_mfma_f32_16x16x32_bf16 v[62:65], v[162:165], v[188:191], v[62:65]
	v_mfma_f32_16x16x32_bf16 v[58:61], v[170:173], v[188:191], v[58:61]
	v_mfma_f32_16x16x32_bf16 v[46:49], v[162:165], v[196:199], v[46:49]
	v_mfma_f32_16x16x32_bf16 v[42:45], v[170:173], v[196:199], v[42:45]
	v_mfma_f32_16x16x32_bf16 v[30:33], v[162:165], v[204:207], v[30:33]
	v_mfma_f32_16x16x32_bf16 v[26:29], v[170:173], v[204:207], v[26:29]
	v_mfma_f32_16x16x32_bf16 v[14:17], v[162:165], v[212:215], v[14:17]
	v_mfma_f32_16x16x32_bf16 v[10:13], v[170:173], v[212:215], v[10:13]
	s_barrier
	s_add_u32 s4, s4, 0x80080
	s_addc_u32 s5, s5, 0
	s_add_i32 s24, s24, s45
	s_mov_b32 m0, s24
	s_nop 0
	global_load_lds_dwordx4 v134, s[4:5]
	s_add_i32 m0, s24, 0x2000
	s_nop 0
	global_load_lds_dwordx4 v130, s[4:5]
	s_waitcnt vmcnt(6)
	s_barrier
	v_mfma_f32_16x16x32_bf16 v[54:57], v[216:219], v[174:177], v[54:57]
	v_mfma_f32_16x16x32_bf16 v[50:53], v[224:227], v[174:177], v[50:53]
	v_mfma_f32_16x16x32_bf16 v[38:41], v[216:219], v[192:195], v[38:41]
	v_mfma_f32_16x16x32_bf16 v[34:37], v[224:227], v[192:195], v[34:37]
	v_mfma_f32_16x16x32_bf16 v[22:25], v[216:219], v[200:203], v[22:25]
	v_mfma_f32_16x16x32_bf16 v[18:21], v[224:227], v[200:203], v[18:21]
	v_mfma_f32_16x16x32_bf16 v[6:9], v[216:219], v[208:211], v[6:9]
	v_mfma_f32_16x16x32_bf16 v[2:5], v[224:227], v[208:211], v[2:5]
	v_mfma_f32_16x16x32_bf16 v[54:57], v[220:223], v[188:191], v[54:57]
	v_mfma_f32_16x16x32_bf16 v[50:53], v[228:231], v[188:191], v[50:53]
	v_mfma_f32_16x16x32_bf16 v[38:41], v[220:223], v[196:199], v[38:41]
	v_mfma_f32_16x16x32_bf16 v[34:37], v[228:231], v[196:199], v[34:37]
	v_mfma_f32_16x16x32_bf16 v[22:25], v[220:223], v[204:207], v[22:25]
	v_mfma_f32_16x16x32_bf16 v[18:21], v[228:231], v[204:207], v[18:21]
	v_mfma_f32_16x16x32_bf16 v[6:9], v[220:223], v[212:215], v[6:9]
	v_mfma_f32_16x16x32_bf16 v[2:5], v[228:231], v[212:215], v[2:5]
	s_add_i32 s59, s59, 2
	s_add_u32 s57, s57, 0x100
	s_addc_u32 s58, s58, 0
	s_cmp_gt_u32 s59, 29
	s_mov_b64 s[38:39], s[42:43]
	s_barrier
	s_cbranch_scc0 .LBB0_158
	v_fmamk_f32 v0, v145, 0x3a000000, v233
	v_cmp_gt_f32_e32 vcc, s66, v0
	v_mul_f32_e32 v145, 0x4b800000, v0
	v_readlane_b32 s38, v254, 47
	v_cndmask_b32_e32 v0, v0, v145, vcc
	v_rsq_f32_e32 v0, v0
	v_lshl_add_u32 v146, s54, 8, v139
	s_cmp_gt_i32 s53, 15
	v_readlane_b32 s39, v254, 48
	v_mul_f32_e32 v145, 0x45800000, v0
	s_cselect_b64 s[4:5], -1, 0
	s_xor_b64 s[38:39], s[38:39], -1
	v_cndmask_b32_e32 v148, v0, v145, vcc
	v_ashrrev_i32_e32 v147, 31, v146
	s_or_b64 s[4:5], s[38:39], s[4:5]
	v_lshl_or_b32 v144, s53, 8, v153
	v_lshlrev_b64 v[150:151], 14, v[146:147]
	v_pk_mul_f32 v[128:129], v[148:149], v[128:129] op_sel_hi:[0,1]
	s_mov_b64 s[24:25], -1
	v_pk_mul_f32 v[126:127], v[148:149], v[126:127] op_sel_hi:[0,1]
	v_pk_mul_f32 v[162:163], v[148:149], v[124:125] op_sel_hi:[0,1]
	v_pk_mul_f32 v[124:125], v[148:149], v[122:123] op_sel_hi:[0,1]
	v_cvt_pk_bf16_f32 v122, v126, v127
	v_cvt_pk_bf16_f32 v123, v128, v129
	s_and_b64 vcc, exec, s[4:5]
	v_lshl_add_u64 v[128:129], s[16:17], 0, v[150:151]
	v_ashrrev_i32_e32 v145, 31, v144
	v_cvt_pk_bf16_f32 v124, v124, v125
	v_cvt_pk_bf16_f32 v125, v162, v163
	s_cbranch_vccz .LBB0_161
	v_lshl_add_u64 v[150:151], v[144:145], 1, v[128:129]
	s_mov_b64 s[24:25], 0
